# attention: next q-block key tile 0 (K, rope-K, V, scales) loaded at the epilogue top ahead of the O stores; one prologue wait vmcnt(8)
# baseline (speedup 1.0000x reference)
.LBB0_44:
	s_cmp_eq_u32 s38, 0
	s_cbranch_scc1 .Lq_nopref
	s_add_i32 s53, s38, -1
	s_lshl_b32 s53, s53, 8
	s_add_i32 s53, s35, s53
	v_or_b32_e32 v108, s53, v184
	v_mov_b64_e32 v[110:111], s[50:51]
	v_lshlrev_b32_e32 v112, 3, v185
	v_mad_i64_i32 v[110:111], vcc, v108, s17, v[110:111]
	v_ashrrev_i32_e32 v113, 31, v112
	v_lshl_add_u64 v[110:111], v[112:113], 1, v[110:111]
	global_load_dwordx4 v[84:87], v[110:111], off offset:128
	global_load_dwordx4 v[88:91], v[110:111], off offset:160
	global_load_dwordx4 v[92:95], v[110:111], off offset:96
	global_load_dwordx4 v[118:121], v[110:111], off offset:64
	global_load_dwordx4 v[122:125], v[110:111], off offset:32
	global_load_dwordx4 v[126:129], v[110:111], off
	global_load_dwordx4 v[66:69], v[158:159], off
	s_and_b64 vcc, s[42:43], s[44:45]
	s_and_saveexec_b64 s[48:49], vcc
	global_load_dword v234, v[166:167], off
	global_load_dword v235, v[168:169], off
	s_andn2_b64 exec, s[48:49], s[42:43]
	global_load_dwordx4 v[80:83], v[170:171], off
	s_mov_b64 exec, s[48:49]
	global_load_dwordx4 v[230:233], v[160:161], off

.LBB0_45:
	s_cmp_lg_u32 s38, 7
	s_cbranch_scc1 .Lkv_skip
	global_load_dwordx4 v[66:69], v[158:159], off
	s_and_b64 s[52:53], s[42:43], s[44:45]
	s_and_saveexec_b64 s[48:49], s[52:53]
	global_load_dword v234, v[166:167], off
	global_load_dword v235, v[168:169], off
	s_andn2_b64 exec, s[48:49], s[42:43]
	global_load_dwordx4 v[80:83], v[170:171], off
	s_mov_b64 exec, s[48:49]
	global_load_dwordx4 v[230:233], v[160:161], off
.Lkv_skip:
	s_lshl_b32 s48, s38, 8
	s_add_i32 s52, s35, s48
	v_mov_b32_e32 v1, v185
	v_or_b32_e32 v6, s52, v184
	v_mov_b64_e32 v[8:9], s[50:51]
	v_lshlrev_b32_e32 v18, 3, v1
	v_mad_i64_i32 v[8:9], s[48:49], v6, s17, v[8:9]
	v_ashrrev_i32_e32 v19, 31, v18
	v_lshl_add_u64 v[8:9], v[18:19], 1, v[8:9]
	s_cmp_lg_u32 s38, 7
	s_cbranch_scc1 .Lq_skipQ
	global_load_dwordx4 v[84:87], v[8:9], off offset:128
	global_load_dwordx4 v[88:91], v[8:9], off offset:160
	global_load_dwordx4 v[92:95], v[8:9], off offset:96
	global_load_dwordx4 v[118:121], v[8:9], off offset:64
	global_load_dwordx4 v[122:125], v[8:9], off offset:32
	global_load_dwordx4 v[126:129], v[8:9], off
.Lq_skipQ:
	v_ashrrev_i32_e32 v7, 31, v6
	v_lshlrev_b64 v[6:7], 6, v[6:7]
	v_lshlrev_b64 v[8:9], 2, v[18:19]
	v_lshl_add_u64 v[18:19], s[2:3], 0, v[6:7]
	v_lshl_add_u64 v[6:7], s[4:5], 0, v[6:7]
	v_lshl_add_u32 v1, v1, 5, 0
	v_lshl_add_u64 v[18:19], v[18:19], 0, v[8:9]
	v_lshl_add_u64 v[34:35], v[6:7], 0, v[8:9]
	ds_read_b128 v[70:73], v1 offset:46080
	ds_read_b128 v[62:65], v1 offset:46096
	ds_read_b128 v[58:61], v1 offset:46144
	ds_read_b128 v[54:57], v1 offset:46160
	ds_read_b128 v[50:53], v1 offset:46208
	ds_read_b128 v[46:49], v1 offset:46224
	ds_read_b128 v[42:45], v1 offset:46272
	ds_read_b128 v[38:41], v1 offset:46288
	ds_read_b128 v[30:33], v1 offset:46336
	ds_read_b128 v[14:17], v1 offset:46352
	ds_read_b128 v[22:25], v1 offset:46400
	ds_read_b128 v[10:13], v1 offset:46416
	global_load_dwordx4 v[6:9], v[18:19], off offset:16
	global_load_dwordx4 v[26:29], v[18:19], off
	s_nop 0
	global_load_dwordx4 v[18:21], v[34:35], off offset:16
	s_nop 0
	global_load_dwordx4 v[34:37], v[34:35], off
	s_cbranch_scc1 .Lq_w8
	s_waitcnt vmcnt(4)
	s_branch .Lq_wd
.Lq_w8:
	s_waitcnt vmcnt(8)
.Lq_wd:
	s_nop 0
	v_lshlrev_b32_e32 v74, 16, v87
	v_and_b32_e32 v75, 0xffff0000, v87
	v_lshlrev_b32_e32 v78, 16, v86
	v_and_b32_e32 v79, 0xffff0000, v86
	v_lshlrev_b32_e32 v86, 16, v93
	v_and_b32_e32 v87, 0xffff0000, v93
	v_lshlrev_b32_e32 v112, 16, v92
	v_and_b32_e32 v113, 0xffff0000, v92
	v_lshlrev_b32_e32 v92, 16, v125
	v_and_b32_e32 v93, 0xffff0000, v125
	v_and_b32_e32 v125, 0xffff0000, v126
	v_lshlrev_b32_e32 v98, 16, v119
	v_and_b32_e32 v99, 0xffff0000, v119
	v_lshlrev_b32_e32 v116, 16, v118
	v_and_b32_e32 v117, 0xffff0000, v118
	v_lshlrev_b32_e32 v118, 16, v124
	v_and_b32_e32 v119, 0xffff0000, v124
	v_lshlrev_b32_e32 v124, 16, v126
	v_mul_f32_e32 v1, v125, v125
	v_lshlrev_b32_e32 v100, 16, v90
	v_and_b32_e32 v101, 0xffff0000, v90
	v_lshlrev_b32_e32 v90, 16, v127
	v_fmac_f32_e32 v1, v124, v124
	v_lshlrev_b32_e32 v76, 16, v91
	v_and_b32_e32 v77, 0xffff0000, v91
	v_and_b32_e32 v91, 0xffff0000, v127
	v_fmac_f32_e32 v1, v90, v90
	v_lshlrev_b32_e32 v96, 16, v121
	v_and_b32_e32 v97, 0xffff0000, v121
	v_lshlrev_b32_e32 v114, 16, v120
	v_and_b32_e32 v115, 0xffff0000, v120
	v_lshlrev_b32_e32 v120, 16, v122
	v_and_b32_e32 v121, 0xffff0000, v122
	v_lshlrev_b32_e32 v122, 16, v128
	v_fmac_f32_e32 v1, v91, v91
	v_lshlrev_b32_e32 v102, 16, v85
	v_and_b32_e32 v103, 0xffff0000, v85
	v_lshlrev_b32_e32 v106, 16, v84
	v_and_b32_e32 v107, 0xffff0000, v84
	v_lshlrev_b32_e32 v84, 16, v95
	v_and_b32_e32 v85, 0xffff0000, v95
	v_lshlrev_b32_e32 v110, 16, v94
	v_and_b32_e32 v111, 0xffff0000, v94
	v_lshlrev_b32_e32 v94, 16, v123
	v_and_b32_e32 v95, 0xffff0000, v123
	v_and_b32_e32 v123, 0xffff0000, v128
	v_fmac_f32_e32 v1, v122, v122
	v_lshlrev_b32_e32 v108, 16, v88
	v_and_b32_e32 v109, 0xffff0000, v88
	v_lshlrev_b32_e32 v88, 16, v129
	v_fmac_f32_e32 v1, v123, v123
	v_lshlrev_b32_e32 v104, 16, v89
	v_and_b32_e32 v105, 0xffff0000, v89
	v_and_b32_e32 v89, 0xffff0000, v129
	v_fmac_f32_e32 v1, v88, v88
	v_fmac_f32_e32 v1, v89, v89
	v_fmac_f32_e32 v1, v120, v120
	v_fmac_f32_e32 v1, v121, v121
	v_fmac_f32_e32 v1, v94, v94
	v_fmac_f32_e32 v1, v95, v95
	v_fmac_f32_e32 v1, v118, v118
	v_fmac_f32_e32 v1, v119, v119
	v_fmac_f32_e32 v1, v92, v92
	v_fmac_f32_e32 v1, v93, v93
	v_fmac_f32_e32 v1, v116, v116
	v_fmac_f32_e32 v1, v117, v117
	v_fmac_f32_e32 v1, v98, v98
	v_fmac_f32_e32 v1, v99, v99
	v_fmac_f32_e32 v1, v114, v114
	v_fmac_f32_e32 v1, v115, v115
	v_fmac_f32_e32 v1, v96, v96
	v_fmac_f32_e32 v1, v97, v97
	v_fmac_f32_e32 v1, v112, v112
	v_fmac_f32_e32 v1, v113, v113
	v_fmac_f32_e32 v1, v86, v86
	v_fmac_f32_e32 v1, v87, v87
	v_fmac_f32_e32 v1, v110, v110
	v_fmac_f32_e32 v1, v111, v111
	v_fmac_f32_e32 v1, v84, v84
	v_pk_mul_f32 v[210:211], v[106:107], v[106:107]
	v_fmac_f32_e32 v1, v85, v85
	v_add_f32_e32 v1, v1, v210
	v_pk_mul_f32 v[180:181], v[102:103], v[102:103]
	v_add_f32_e32 v1, v1, v211
	v_add_f32_e32 v1, v1, v180
	v_pk_mul_f32 v[176:177], v[78:79], v[78:79]
	v_add_f32_e32 v1, v1, v181
	v_add_f32_e32 v1, v1, v176
	v_pk_mul_f32 v[130:131], v[74:75], v[74:75]
	v_add_f32_e32 v1, v1, v177
	v_add_f32_e32 v1, v1, v130
	v_pk_mul_f32 v[212:213], v[108:109], v[108:109]
	v_add_f32_e32 v1, v1, v131
	v_add_f32_e32 v1, v1, v212
	v_pk_mul_f32 v[182:183], v[104:105], v[104:105]
	v_add_f32_e32 v1, v1, v213
	v_add_f32_e32 v1, v1, v182
	v_pk_mul_f32 v[178:179], v[100:101], v[100:101]
	v_add_f32_e32 v1, v1, v183
	v_add_f32_e32 v1, v1, v178
	v_pk_mul_f32 v[174:175], v[76:77], v[76:77]
	v_add_f32_e32 v1, v1, v179
	v_add_f32_e32 v1, v1, v174
	v_add_f32_e32 v1, v1, v175
	v_mov_b32_e32 v126, v1
	s_nop 1
	v_permlane32_swap_b32_e32 v1, v126
	v_add_u32_e32 v127, v186, v134
	ds_write_b128 v127, v[66:69]
	s_and_saveexec_b64 s[48:49], s[42:43]
	s_xor_b64 s[54:55], exec, s[48:49]
	s_cbranch_execz .LBB0_55
	s_and_saveexec_b64 s[56:57], s[44:45]
	s_cbranch_execz .LBB0_54
	v_add_f32_e32 v66, v234, v235
	v_fmamk_f32 v66, v66, 0x3c2aaaab, v207
	v_rsq_f32_e32 v66, v66
	v_add_u32_e32 v67, 0, v187
	ds_write_b32 v67, v66 offset:21504

.LBB0_55:
	s_andn2_saveexec_b64 s[54:55], s[54:55]
	ds_write_b128 v197, v[80:83] offset:128
	s_or_b64 exec, exec, s[54:55]
	v_add_f32_e32 v1, v1, v126
	v_fmamk_f32 v1, v1, 0x3c2aaaab, v207
	v_rsq_f32_e32 v1, v1
	ds_write_b128 v198, v[230:233] offset:13312
	s_waitcnt lgkmcnt(0)
	s_barrier
	v_mul_f32_e32 v66, 0x3e16c740, v1
	s_waitcnt lgkmcnt(6)
	v_pk_mul_f32 v[38:39], v[66:67], v[38:39] op_sel_hi:[0,1]
	v_pk_mul_f32 v[38:39], v[38:39], v[110:111]
	v_pk_mul_f32 v[44:45], v[66:67], v[44:45] op_sel_hi:[0,1]
	v_pk_mul_f32 v[44:45], v[44:45], v[86:87]
	v_cvt_pk_bf16_f32 v86, v38, v39
	v_pk_mul_f32 v[38:39], v[66:67], v[106:107] op_sel_hi:[0,1]
	s_waitcnt lgkmcnt(5)
	v_pk_mul_f32 v[30:31], v[38:39], v[30:31]
	v_pk_mul_f32 v[38:39], v[66:67], v[108:109] op_sel_hi:[0,1]
	s_waitcnt lgkmcnt(3)
	v_pk_mul_f32 v[22:23], v[38:39], v[22:23]
	v_pk_mul_f32 v[46:47], v[66:67], v[46:47] op_sel_hi:[0,1]
	s_waitcnt vmcnt(0)
	v_pk_mul_f32 v[38:39], v[22:23], v[34:35]
	v_pk_mul_f32 v[42:43], v[66:67], v[42:43] op_sel_hi:[0,1]
	v_pk_fma_f32 v[38:39], v[30:31], v[26:27], v[38:39] neg_lo:[0,0,1] neg_hi:[0,0,1]
	v_pk_mul_f32 v[30:31], v[30:31], v[34:35]
	v_pk_mul_f32 v[40:41], v[66:67], v[40:41] op_sel_hi:[0,1]
	v_pk_fma_f32 v[22:23], v[22:23], v[26:27], v[30:31]
	v_pk_mul_f32 v[30:31], v[66:67], v[104:105] op_sel_hi:[0,1]
	v_pk_mul_f32 v[26:27], v[66:67], v[102:103] op_sel_hi:[0,1]
	v_pk_mul_f32 v[24:25], v[30:31], v[24:25]
	v_pk_mul_f32 v[26:27], v[26:27], v[32:33]
	v_pk_mul_f32 v[30:31], v[24:25], v[36:37]
	v_pk_mul_f32 v[68:69], v[66:67], v[70:71] op_sel_hi:[0,1]
	v_pk_fma_f32 v[30:31], v[26:27], v[28:29], v[30:31] neg_lo:[0,0,1] neg_hi:[0,0,1]
	v_pk_mul_f32 v[26:27], v[26:27], v[36:37]
	v_pk_mul_f32 v[62:63], v[66:67], v[62:63] op_sel_hi:[0,1]
	v_pk_fma_f32 v[24:25], v[24:25], v[28:29], v[26:27]
	v_pk_mul_f32 v[26:27], v[66:67], v[78:79] op_sel_hi:[0,1]
	v_pk_mul_f32 v[14:15], v[26:27], v[14:15]
	v_pk_mul_f32 v[26:27], v[66:67], v[100:101] op_sel_hi:[0,1]
	s_waitcnt lgkmcnt(2)
	v_pk_mul_f32 v[10:11], v[26:27], v[10:11]
	v_pk_mul_f32 v[70:71], v[66:67], v[72:73] op_sel_hi:[0,1]
	v_pk_mul_f32 v[26:27], v[10:11], v[18:19]
	v_pk_mul_f32 v[64:65], v[66:67], v[64:65] op_sel_hi:[0,1]
	v_pk_fma_f32 v[26:27], v[14:15], v[6:7], v[26:27] neg_lo:[0,0,1] neg_hi:[0,0,1]
	v_pk_mul_f32 v[14:15], v[14:15], v[18:19]
	v_pk_mul_f32 v[58:59], v[66:67], v[58:59] op_sel_hi:[0,1]
	v_pk_fma_f32 v[6:7], v[10:11], v[6:7], v[14:15]
	v_pk_mul_f32 v[14:15], v[66:67], v[76:77] op_sel_hi:[0,1]
	v_pk_mul_f32 v[10:11], v[66:67], v[74:75] op_sel_hi:[0,1]
	v_pk_mul_f32 v[12:13], v[14:15], v[12:13]
	v_pk_mul_f32 v[10:11], v[10:11], v[16:17]
	v_pk_mul_f32 v[14:15], v[12:13], v[20:21]
	v_pk_mul_f32 v[54:55], v[66:67], v[54:55] op_sel_hi:[0,1]
	v_pk_fma_f32 v[14:15], v[10:11], v[8:9], v[14:15] neg_lo:[0,0,1] neg_hi:[0,0,1]
	v_pk_mul_f32 v[10:11], v[10:11], v[20:21]
	v_pk_mul_f32 v[60:61], v[66:67], v[60:61] op_sel_hi:[0,1]
	v_pk_mul_f32 v[56:57], v[66:67], v[56:57] op_sel_hi:[0,1]
	v_pk_mul_f32 v[50:51], v[66:67], v[50:51] op_sel_hi:[0,1]
	v_pk_mul_f32 v[46:47], v[46:47], v[114:115]
	v_pk_mul_f32 v[52:53], v[66:67], v[52:53] op_sel_hi:[0,1]
	v_pk_mul_f32 v[48:49], v[66:67], v[48:49] op_sel_hi:[0,1]
	v_pk_mul_f32 v[42:43], v[42:43], v[112:113]
	v_pk_mul_f32 v[40:41], v[40:41], v[84:85]
	v_pk_fma_f32 v[8:9], v[12:13], v[8:9], v[10:11]
	v_cvt_pk_bf16_f32 v103, v14, v15
	v_mov_b32_e32 v14, v0
	v_mov_b32_e32 v15, v0
	v_pk_mul_f32 v[68:69], v[68:69], v[124:125]
	v_pk_mul_f32 v[62:63], v[62:63], v[122:123]
	v_pk_mul_f32 v[70:71], v[70:71], v[90:91]
	v_pk_mul_f32 v[64:65], v[64:65], v[88:89]
	v_pk_mul_f32 v[58:59], v[58:59], v[120:121]
	v_pk_mul_f32 v[54:55], v[54:55], v[118:119]
	v_pk_mul_f32 v[60:61], v[60:61], v[94:95]
	v_pk_mul_f32 v[56:57], v[56:57], v[92:93]
	v_pk_mul_f32 v[50:51], v[50:51], v[116:117]
	v_pk_mul_f32 v[52:53], v[52:53], v[98:99]
	v_pk_mul_f32 v[48:49], v[48:49], v[96:97]
	v_cvt_pk_bf16_f32 v98, v46, v47
	v_cvt_pk_bf16_f32 v84, v42, v43
	v_cvt_pk_bf16_f32 v85, v44, v45
	v_cvt_pk_bf16_f32 v87, v40, v41
	v_cvt_pk_bf16_f32 v100, v38, v39
	v_cvt_pk_bf16_f32 v101, v30, v31
	v_cvt_pk_bf16_f32 v102, v26, v27
	v_cvt_pk_bf16_f32 v104, v22, v23
	v_cvt_pk_bf16_f32 v105, v24, v25
	v_cvt_pk_bf16_f32 v106, v6, v7
	v_cvt_pk_bf16_f32 v107, v8, v9
	s_lshl_b32 s48, s38, 2
	v_mov_b32_e32 v1, v0
	v_mov_b32_e32 v2, v0
	v_mov_b32_e32 v3, v0
	v_mov_b32_e32 v4, v0
	v_mov_b32_e32 v5, v0
	v_mov_b32_e32 v6, v0
	v_mov_b32_e32 v7, v0
	v_mov_b32_e32 v8, v0
	v_mov_b32_e32 v9, v0
	v_mov_b32_e32 v10, v0
	v_mov_b32_e32 v11, v0
	v_mov_b32_e32 v12, v0
	v_mov_b32_e32 v13, v0
	v_mov_b64_e32 v[30:31], v[14:15]
	v_mov_b64_e32 v[46:47], v[14:15]
	v_cvt_pk_bf16_f32 v88, v68, v69
	v_cvt_pk_bf16_f32 v89, v70, v71
	v_cvt_pk_bf16_f32 v90, v62, v63
	v_cvt_pk_bf16_f32 v91, v64, v65
	v_cvt_pk_bf16_f32 v92, v58, v59
	v_cvt_pk_bf16_f32 v93, v60, v61
	v_cvt_pk_bf16_f32 v94, v54, v55
	v_cvt_pk_bf16_f32 v95, v56, v57
	v_cvt_pk_bf16_f32 v96, v50, v51
	v_cvt_pk_bf16_f32 v97, v52, v53
	v_cvt_pk_bf16_f32 v99, v48, v49
	s_add_i32 s48, s48, s26
	s_mov_b32 s49, 0
	v_mov_b32_e32 v151, 0
	v_mov_b64_e32 v[174:175], v[172:173]
	v_mov_b32_e32 v176, v228
	v_mov_b32_e32 v178, v205
	v_mov_b32_e32 v180, v204
	v_mov_b64_e32 v[182:183], v[146:147]
	v_mov_b64_e32 v[28:29], v[12:13]
	v_mov_b64_e32 v[26:27], v[10:11]
	v_mov_b64_e32 v[24:25], v[8:9]
	v_mov_b64_e32 v[22:23], v[6:7]
	v_mov_b64_e32 v[20:21], v[4:5]
	v_mov_b64_e32 v[18:19], v[2:3]
	v_mov_b64_e32 v[16:17], v[0:1]
	v_mov_b64_e32 v[44:45], v[12:13]
	v_mov_b64_e32 v[42:43], v[10:11]
	v_mov_b64_e32 v[40:41], v[8:9]
	v_mov_b64_e32 v[38:39], v[6:7]
	v_mov_b64_e32 v[36:37], v[4:5]
	v_mov_b64_e32 v[34:35], v[2:3]
	v_mov_b64_e32 v[32:33], v[0:1]
	v_lshlrev_b32_e32 v1, 4, v164
	v_add_u32_e32 v1, 0x14000, v1
	ds_write_b128 v1, v[194:197]
	ds_write_b128 v1, v[198:201] offset:8192
	ds_write_b128 v1, v[202:205] offset:16384
	s_waitcnt lgkmcnt(0)
	s_cmp_lg_u64 s[42:43], 0
	s_cbranch_scc1 .Latt2_h1
	global_load_dwordx4 v[194:197], v[182:183], off
	v_ashrrev_i32_e32 v177, 31, v176
	v_lshlrev_b64 v[202:203], 6, v[176:177]
	v_lshl_add_u64 v[202:203], v[144:145], 0, v[202:203]
	global_load_dwordx4 v[198:201], v[202:203], off
	global_load_dwordx4 v[202:205], v[174:175], off
	v_lshl_add_u64 v[182:183], v[182:183], 0, s[10:11]
	v_add_u32_e32 v180, 0x400, v180
	v_add_u32_e32 v178, 64, v178
	v_add_u32_e32 v176, 64, v176
	v_lshl_add_u64 v[174:175], v[174:175], 0, s[12:13]
	global_load_dwordx4 v[2:5], v[182:183], off
	v_ashrrev_i32_e32 v177, 31, v176
	v_lshlrev_b64 v[6:7], 6, v[176:177]
	v_lshl_add_u64 v[6:7], v[144:145], 0, v[6:7]
	global_load_dwordx4 v[80:83], v[6:7], off
	global_load_dwordx4 v[6:9], v[174:175], off
	v_lshl_add_u64 v[182:183], v[182:183], 0, s[10:11]
	v_add_u32_e32 v180, 0x400, v180
	v_add_u32_e32 v178, 64, v178
	v_add_u32_e32 v176, 64, v176
	v_lshl_add_u64 v[174:175], v[174:175], 0, s[12:13]
